# v64 + slabsum_pf (w_out context slab-sum: 4 slab loads issued together, counted waits, same add order)
# baseline (speedup 1.0000x reference)
; __device__ __forceinline__ unsigned cvt_pk_bf16(float lo, float hi) { unsigned r; asm volatile("v_cvt_pk_bf16_f32 %0, %1, %2" : "=v"(r) : "v"(lo), "v"(hi)); return r; }
; __device__ __forceinline__ float bflo(unsigned w) { return __uint_as_float(w << 16); }
; __device__ __forceinline__ float bfhi(unsigned w) { return __uint_as_float(w & 0xffff0000u); }
; __global__ void __launch_bounds__(512, 2) fwd_kernel(Params prm) {
;     ...
;         case 4: { if (!lastl) {
;                       const bf16_t* SLg = Hl; bf16_t* Gc = Gb + (size_t)ML * 1024;
;                       for (int i = F.bid * 512 + F.tid; i < 1024 * 1024 / 8; i += F.G * 512) { f32x4 a0 = {0.f, 0.f, 0.f, 0.f}, a1 = a0;
; #pragma unroll
;                           for (int sl = 0; sl < 4; ++sl) { const u32x4 w = *(const u32x4*)(SLg + (size_t)sl * (1024 * 1024) + (size_t)i * 8);
;                               a0 = a0 + (f32x4){bflo(w.x), bfhi(w.x), bflo(w.y), bfhi(w.y)}; a1 = a1 + (f32x4){bflo(w.z), bfhi(w.z), bflo(w.w), bfhi(w.w)}; }
;                           u32x4 o; o.x = cvt_pk_bf16(a0[0], a0[1]); o.y = cvt_pk_bf16(a0[2], a0[3]); o.z = cvt_pk_bf16(a1[0], a1[1]); o.w = cvt_pk_bf16(a1[2], a1[3]);
;                           *(u32x4*)(Gc + (size_t)i * 8) = o; }
.LBB0_257:
	v_lshl_add_u64 v[8:9], s[54:55], 0, v[2:3]
	global_load_dwordx4 v[4:7], v[8:9], off
	v_add_co_u32_e32 v20, vcc, s18, v8
	v_add_u32_e32 v0, s8, v0
	s_mov_b32 s0, 0x1ffff
	v_addc_co_u32_e32 v21, vcc, 0, v9, vcc
	global_load_dwordx4 v[20:23], v[20:21], off
	v_add_co_u32_e32 v24, vcc, s19, v8
	s_nop 1
	v_addc_co_u32_e32 v25, vcc, 0, v9, vcc
	global_load_dwordx4 v[24:27], v[24:25], off
	v_add_co_u32_e32 v28, vcc, s22, v8
	s_nop 1
	v_addc_co_u32_e32 v29, vcc, 0, v9, vcc
	global_load_dwordx4 v[28:31], v[28:29], off
	s_waitcnt vmcnt(3)
	v_lshlrev_b32_e32 v18, 16, v4
	v_and_b32_e32 v19, 0xffff0000, v4
	v_pk_add_f32 v[10:11], v[18:19], 0 op_sel_hi:[1,0]
	v_lshlrev_b32_e32 v18, 16, v5
	v_and_b32_e32 v19, 0xffff0000, v5
	v_pk_add_f32 v[12:13], v[18:19], 0 op_sel_hi:[1,0]
	v_lshlrev_b32_e32 v18, 16, v6
	v_and_b32_e32 v19, 0xffff0000, v6
	v_pk_add_f32 v[14:15], v[18:19], 0 op_sel_hi:[1,0]
	v_lshlrev_b32_e32 v18, 16, v7
	v_and_b32_e32 v19, 0xffff0000, v7
	v_pk_add_f32 v[16:17], v[18:19], 0 op_sel_hi:[1,0]
	s_waitcnt vmcnt(2)
	v_lshlrev_b32_e32 v18, 16, v20
	v_and_b32_e32 v19, 0xffff0000, v20
	v_pk_add_f32 v[10:11], v[10:11], v[18:19]
	v_lshlrev_b32_e32 v18, 16, v21
	v_and_b32_e32 v19, 0xffff0000, v21
	v_pk_add_f32 v[12:13], v[12:13], v[18:19]
	v_lshlrev_b32_e32 v18, 16, v22
	v_and_b32_e32 v19, 0xffff0000, v22
	v_pk_add_f32 v[14:15], v[14:15], v[18:19]
	v_lshlrev_b32_e32 v18, 16, v23
	v_and_b32_e32 v19, 0xffff0000, v23
	v_pk_add_f32 v[16:17], v[16:17], v[18:19]
	s_waitcnt vmcnt(1)
	v_lshlrev_b32_e32 v18, 16, v24
	v_and_b32_e32 v19, 0xffff0000, v24
	v_pk_add_f32 v[10:11], v[10:11], v[18:19]
	v_lshlrev_b32_e32 v18, 16, v25
	v_and_b32_e32 v19, 0xffff0000, v25
	v_pk_add_f32 v[12:13], v[12:13], v[18:19]
	v_lshlrev_b32_e32 v18, 16, v26
	v_and_b32_e32 v19, 0xffff0000, v26
	v_pk_add_f32 v[14:15], v[14:15], v[18:19]
	v_lshlrev_b32_e32 v18, 16, v27
	v_and_b32_e32 v19, 0xffff0000, v27
	v_pk_add_f32 v[16:17], v[16:17], v[18:19]
	s_waitcnt vmcnt(0)
	v_lshlrev_b32_e32 v18, 16, v28
	v_and_b32_e32 v19, 0xffff0000, v28
	v_pk_add_f32 v[10:11], v[10:11], v[18:19]
	v_lshlrev_b32_e32 v18, 16, v29
	v_and_b32_e32 v19, 0xffff0000, v29
	v_pk_add_f32 v[12:13], v[12:13], v[18:19]
	v_lshlrev_b32_e32 v18, 16, v30
	v_and_b32_e32 v19, 0xffff0000, v30
	v_pk_add_f32 v[14:15], v[14:15], v[18:19]
	v_lshlrev_b32_e32 v18, 16, v31
	v_and_b32_e32 v19, 0xffff0000, v31
	v_pk_add_f32 v[16:17], v[16:17], v[18:19]
	v_cmp_lt_i32_e32 vcc, s0, v0
	s_or_b64 s[24:25], vcc, s[24:25]
	v_lshl_add_u64 v[8:9], s[20:21], 0, v[2:3]
	v_lshl_add_u64 v[2:3], v[2:3], 0, s[12:13]
	v_cvt_pk_bf16_f32 v4, v10, v11
	v_cvt_pk_bf16_f32 v5, v12, v13
	v_cvt_pk_bf16_f32 v6, v14, v15
	v_cvt_pk_bf16_f32 v7, v16, v17
	global_store_dwordx4 v[8:9], v[4:7], off
	s_andn2_b64 exec, exec, s[24:25]
	s_cbranch_execnz .LBB0_257
